# UPCONV: sum-of-squares words for the epilogue requested in the last K iteration into K-loop-free registers
# baseline (speedup 1.0000x reference)
; #define PG8_STAGE(bufoff, gbase, voff) do { _Pragma("unroll") for (int _i = 0; _i < 2; ++_i) \
;         __builtin_amdgcn_global_load_lds((const unsigned*)((const char*)(gbase) + (voff)[_i]), (PG8_LAS unsigned*)(lds + (bufoff) + ldsw + _i * 8192), 16, 0, 0); } while (0)
; #define PG8_LDA(dst, b, h) do { _Pragma("unroll") for (int m = 0; m < 4; ++m) _Pragma("unroll") for (int k = 0; k < 2; ++k) dst[m][k] = *(const PG8_LAS bf16x8*)(lds + PG8_SA(b, h) + aoff + m * 2048 + k * 1024); } while (0)
; #define PG8_LDB(dst, b, h) do { _Pragma("unroll") for (int n = 0; n < 2; ++n) _Pragma("unroll") for (int k = 0; k < 2; ++k) dst[n][k] = *(const PG8_LAS bf16x8*)(lds + PG8_SB(b, h) + boff + n * 2048 + k * 1024); } while (0)
; #define PG8_MMA(ai, bj, At, Bt) do { __builtin_amdgcn_s_setprio(1); _Pragma("unroll") for (int m = 0; m < 4; ++m) _Pragma("unroll") for (int n = 0; n < 2; ++n) _Pragma("unroll") for (int k = 0; k < 2; ++k) \
;         acc[ai][bj][m][n] = __builtin_amdgcn_mfma_f32_16x16x32_bf16(Bt[n][k], At[m][k], acc[ai][bj][m][n], 0, 0, 0); __builtin_amdgcn_s_setprio(0); } while (0)
; #define PG8_WAIT_V(n) asm volatile("s_waitcnt vmcnt(" #n ")" ::: "memory")
; #define PG8_WAIT_L(n) asm volatile("s_waitcnt lgkmcnt(" #n ")" ::: "memory")
; #define PG8_BAR __builtin_amdgcn_s_barrier()
; #define PG8_SCHED __builtin_amdgcn_sched_barrier(0)
; template <class Epi, class Sched, bool ALIGN_EPI = false, bool SP2 = false>
; __device__ __forceinline__ void gemm_phase(PG8_LAS unsigned char* lds, const Gemm g, const Sched& S, const Epi& E, int wave_in) {
;     ...
;             PG8_LDB(B0, 0, 0); PG8_LDB(B1, 0, 1); PG8_SCHED; PG8_LDA(At, 0, 0); PG8_STAGE(PG8_SA(1, 1), a1 + hstepA, voffA);
;             PG8_WAIT_V(8); PG8_WAIT_L(0); PG8_BAR; PG8_MMA(0, 0, At, B0); PG8_MMA(0, 1, At, B1); PG8_BAR; PG8_SCHED;
;             PG8_LDA(At, 0, 1); PG8_STAGE(PG8_SB(0, 0), b2, voffB); PG8_STAGE(PG8_SB(0, 1), b2 + hstep, voffB); PG8_STAGE(PG8_SA(0, 0), a2, voffA);
;             PG8_WAIT_V(8); PG8_WAIT_L(0); PG8_BAR; PG8_MMA(1, 0, At, B0); PG8_MMA(1, 1, At, B1); PG8_BAR; PG8_SCHED;
.LBB0_43:
	s_add_u32 s50, s48, 0xfff80080
	s_addc_u32 s51, s49, -1
	s_add_i32 s72, 0, 0x10000
	s_cmp_eq_u32 s71, 28
	s_cselect_b32 s53, s43, s51
	s_cselect_b32 s52, s67, s50
	s_cselect_b32 s51, s41, s70
	s_cselect_b32 s50, s68, s69
	s_add_i32 s74, 0, 0x14000
	v_add_u32_e32 v118, s72, v214
	v_add_u32_e32 v178, s74, v214
	ds_read_b128 v[106:109], v118
	ds_read_b128 v[110:113], v118 offset:1024
	ds_read_b128 v[114:117], v118 offset:2048
	ds_read_b128 v[118:121], v118 offset:3072
	ds_read_b128 v[122:125], v178
	ds_read_b128 v[126:129], v178 offset:1024
	ds_read_b128 v[130:133], v178 offset:2048
	ds_read_b128 v[178:181], v178 offset:3072
	v_lshl_add_u64 v[238:239], s[48:49], 0, v[174:175]
	s_add_i32 m0, s58, 0xc000
	ds_read_b128 v[182:185], v217
	ds_read_b128 v[186:189], v217 offset:1024
	ds_read_b128 v[190:193], v217 offset:2048
	ds_read_b128 v[218:221], v217 offset:3072
	ds_read_b128 v[222:225], v217 offset:4096
	ds_read_b128 v[226:229], v217 offset:5120
	ds_read_b128 v[230:233], v217 offset:6144
	ds_read_b128 v[234:237], v217 offset:7168
	global_load_lds_dwordx4 v[238:239], off
	v_lshl_add_u64 v[238:239], s[48:49], 0, v[176:177]
	s_add_i32 m0, s58, 0xe000
	s_nop 0
	global_load_lds_dwordx4 v[238:239], off
	s_waitcnt vmcnt(8)
	s_waitcnt lgkmcnt(0)
	s_barrier
	s_waitcnt lgkmcnt(0)
	v_mfma_f32_16x16x32_bf16 v[154:157], v[106:109], v[182:185], v[154:157]
	v_mfma_f32_16x16x32_bf16 v[62:65], v[114:117], v[182:185], v[62:65]
	v_mfma_f32_16x16x32_bf16 v[150:153], v[106:109], v[190:193], v[150:153]
	v_mfma_f32_16x16x32_bf16 v[54:57], v[114:117], v[190:193], v[54:57]
	v_mfma_f32_16x16x32_bf16 v[142:145], v[106:109], v[222:225], v[142:145]
	v_mfma_f32_16x16x32_bf16 v[46:49], v[114:117], v[222:225], v[46:49]
	v_mfma_f32_16x16x32_bf16 v[102:105], v[106:109], v[230:233], v[102:105]
	v_mfma_f32_16x16x32_bf16 v[38:41], v[114:117], v[230:233], v[38:41]
	v_mfma_f32_16x16x32_bf16 v[154:157], v[110:113], v[186:189], v[154:157]
	v_mfma_f32_16x16x32_bf16 v[62:65], v[118:121], v[186:189], v[62:65]
	v_mfma_f32_16x16x32_bf16 v[150:153], v[110:113], v[218:221], v[150:153]
	v_mfma_f32_16x16x32_bf16 v[54:57], v[118:121], v[218:221], v[54:57]
	v_mfma_f32_16x16x32_bf16 v[142:145], v[110:113], v[226:229], v[142:145]
	v_mfma_f32_16x16x32_bf16 v[46:49], v[118:121], v[226:229], v[46:49]
	v_mfma_f32_16x16x32_bf16 v[102:105], v[110:113], v[234:237], v[102:105]
	v_mfma_f32_16x16x32_bf16 v[38:41], v[118:121], v[234:237], v[38:41]
	v_mfma_f32_16x16x32_bf16 v[134:137], v[122:125], v[182:185], v[134:137]
	v_mfma_f32_16x16x32_bf16 v[58:61], v[130:133], v[182:185], v[58:61]
	v_mfma_f32_16x16x32_bf16 v[146:149], v[122:125], v[190:193], v[146:149]
	v_mfma_f32_16x16x32_bf16 v[50:53], v[130:133], v[190:193], v[50:53]
	v_mfma_f32_16x16x32_bf16 v[138:141], v[122:125], v[222:225], v[138:141]
	v_mfma_f32_16x16x32_bf16 v[42:45], v[130:133], v[222:225], v[42:45]
	v_mfma_f32_16x16x32_bf16 v[98:101], v[122:125], v[230:233], v[98:101]
	v_mfma_f32_16x16x32_bf16 v[34:37], v[130:133], v[230:233], v[34:37]
	v_mfma_f32_16x16x32_bf16 v[134:137], v[126:129], v[186:189], v[134:137]
	v_mfma_f32_16x16x32_bf16 v[58:61], v[178:181], v[186:189], v[58:61]
	v_mfma_f32_16x16x32_bf16 v[146:149], v[126:129], v[218:221], v[146:149]
	v_mfma_f32_16x16x32_bf16 v[50:53], v[178:181], v[218:221], v[50:53]
	v_mfma_f32_16x16x32_bf16 v[138:141], v[126:129], v[226:229], v[138:141]
	v_mfma_f32_16x16x32_bf16 v[42:45], v[178:181], v[226:229], v[42:45]
	v_mfma_f32_16x16x32_bf16 v[98:101], v[126:129], v[234:237], v[98:101]
	v_mfma_f32_16x16x32_bf16 v[34:37], v[178:181], v[234:237], v[34:37]
	s_barrier
	s_add_i32 s72, s72, s57
	v_lshl_add_u64 v[238:239], s[50:51], 0, v[0:1]
	s_mov_b32 m0, s72
	ds_read_b128 v[182:185], v217 offset:16384
	ds_read_b128 v[186:189], v217 offset:17408
	ds_read_b128 v[190:193], v217 offset:18432
	ds_read_b128 v[218:221], v217 offset:19456
	ds_read_b128 v[222:225], v217 offset:20480
	ds_read_b128 v[226:229], v217 offset:21504
	ds_read_b128 v[230:233], v217 offset:22528
	ds_read_b128 v[234:237], v217 offset:23552
	global_load_lds_dwordx4 v[238:239], off
	s_add_i32 m0, s72, 0x2000
	s_add_u32 s72, s50, 0x80000
	v_lshl_add_u64 v[240:241], s[50:51], 0, v[168:169]
	s_addc_u32 s73, s51, 0
	s_add_i32 s74, s74, s57
	global_load_lds_dwordx4 v[240:241], off
	v_lshl_add_u64 v[242:243], s[72:73], 0, v[0:1]
	s_mov_b32 m0, s74
	v_lshl_add_u64 v[244:245], s[52:53], 0, v[170:171]
	global_load_lds_dwordx4 v[242:243], off
	v_lshl_add_u64 v[242:243], s[72:73], 0, v[168:169]
	s_add_i32 m0, s74, 0x2000
	s_nop 0
	global_load_lds_dwordx4 v[242:243], off
	v_lshl_add_u64 v[242:243], s[52:53], 0, v[172:173]
	s_mov_b32 m0, s58
	s_nop 0
	global_load_lds_dwordx4 v[242:243], off
	s_mov_b32 m0, s59
	s_nop 0
	global_load_lds_dwordx4 v[244:245], off
	s_waitcnt vmcnt(8)
	s_waitcnt lgkmcnt(0)
	s_barrier
; #define PG8_STAGE(bufoff, gbase, voff) do { _Pragma("unroll") for (int _i = 0; _i < 2; ++_i) \
;         __builtin_amdgcn_global_load_lds((const unsigned*)((const char*)(gbase) + (voff)[_i]), (PG8_LAS unsigned*)(lds + (bufoff) + ldsw + _i * 8192), 16, 0, 0); } while (0)
; #define PG8_LDA(dst, b, h) do { _Pragma("unroll") for (int m = 0; m < 4; ++m) _Pragma("unroll") for (int k = 0; k < 2; ++k) dst[m][k] = *(const PG8_LAS bf16x8*)(lds + PG8_SA(b, h) + aoff + m * 2048 + k * 1024); } while (0)
; #define PG8_LDB(dst, b, h) do { _Pragma("unroll") for (int n = 0; n < 2; ++n) _Pragma("unroll") for (int k = 0; k < 2; ++k) dst[n][k] = *(const PG8_LAS bf16x8*)(lds + PG8_SB(b, h) + boff + n * 2048 + k * 1024); } while (0)
; #define PG8_MMA(ai, bj, At, Bt) do { __builtin_amdgcn_s_setprio(1); _Pragma("unroll") for (int m = 0; m < 4; ++m) _Pragma("unroll") for (int n = 0; n < 2; ++n) _Pragma("unroll") for (int k = 0; k < 2; ++k) \
;         acc[ai][bj][m][n] = __builtin_amdgcn_mfma_f32_16x16x32_bf16(Bt[n][k], At[m][k], acc[ai][bj][m][n], 0, 0, 0); __builtin_amdgcn_s_setprio(0); } while (0)
; #define PG8_WAIT_V(n) asm volatile("s_waitcnt vmcnt(" #n ")" ::: "memory")
; #define PG8_WAIT_L(n) asm volatile("s_waitcnt lgkmcnt(" #n ")" ::: "memory")
; #define PG8_BAR __builtin_amdgcn_s_barrier()
; #define PG8_SCHED __builtin_amdgcn_sched_barrier(0)
; template <class Epi, class Sched, bool ALIGN_EPI = false, bool SP2 = false>
; __device__ __forceinline__ void gemm_phase(PG8_LAS unsigned char* lds, const Gemm g, const Sched& S, const Epi& E, int wave_in) {
;     ...
;             PG8_WAIT_V(8); PG8_WAIT_L(0); PG8_BAR; PG8_MMA(1, 0, At, B0); PG8_MMA(1, 1, At, B1); PG8_BAR; PG8_SCHED;
;             PG8_LDB(B0, 1, 0); PG8_LDB(B1, 1, 1); PG8_SCHED; PG8_LDA(At, 1, 0); PG8_STAGE(PG8_SA(0, 1), a2 + hstepA, voffA);
;             PG8_WAIT_V(8); PG8_WAIT_L(0); PG8_BAR; PG8_MMA(0, 0, At, B0); PG8_MMA(0, 1, At, B1); PG8_BAR; PG8_SCHED;
;             PG8_LDA(At, 1, 1); PG8_STAGE(PG8_SB(1, 0), b3, voffB); PG8_STAGE(PG8_SB(1, 1), b3 + hstep, voffB); PG8_STAGE(PG8_SA(1, 0), a3, voffA);
	s_waitcnt lgkmcnt(0)
	v_mfma_f32_16x16x32_bf16 v[94:97], v[106:109], v[182:185], v[94:97]
	v_mfma_f32_16x16x32_bf16 v[30:33], v[114:117], v[182:185], v[30:33]
	v_mfma_f32_16x16x32_bf16 v[86:89], v[106:109], v[190:193], v[86:89]
	v_mfma_f32_16x16x32_bf16 v[22:25], v[114:117], v[190:193], v[22:25]
	v_mfma_f32_16x16x32_bf16 v[78:81], v[106:109], v[222:225], v[78:81]
	v_mfma_f32_16x16x32_bf16 v[14:17], v[114:117], v[222:225], v[14:17]
	v_mfma_f32_16x16x32_bf16 v[70:73], v[106:109], v[230:233], v[70:73]
	v_mfma_f32_16x16x32_bf16 v[6:9], v[114:117], v[230:233], v[6:9]
	v_mfma_f32_16x16x32_bf16 v[94:97], v[110:113], v[186:189], v[94:97]
	v_mfma_f32_16x16x32_bf16 v[30:33], v[118:121], v[186:189], v[30:33]
	v_mfma_f32_16x16x32_bf16 v[86:89], v[110:113], v[218:221], v[86:89]
	v_mfma_f32_16x16x32_bf16 v[22:25], v[118:121], v[218:221], v[22:25]
	v_mfma_f32_16x16x32_bf16 v[78:81], v[110:113], v[226:229], v[78:81]
	v_mfma_f32_16x16x32_bf16 v[14:17], v[118:121], v[226:229], v[14:17]
	v_mfma_f32_16x16x32_bf16 v[70:73], v[110:113], v[234:237], v[70:73]
	v_mfma_f32_16x16x32_bf16 v[6:9], v[118:121], v[234:237], v[6:9]
	v_mfma_f32_16x16x32_bf16 v[90:93], v[122:125], v[182:185], v[90:93]
	v_mfma_f32_16x16x32_bf16 v[26:29], v[130:133], v[182:185], v[26:29]
	v_mfma_f32_16x16x32_bf16 v[82:85], v[122:125], v[190:193], v[82:85]
	v_mfma_f32_16x16x32_bf16 v[18:21], v[130:133], v[190:193], v[18:21]
	v_mfma_f32_16x16x32_bf16 v[74:77], v[122:125], v[222:225], v[74:77]
	v_mfma_f32_16x16x32_bf16 v[10:13], v[130:133], v[222:225], v[10:13]
	v_mfma_f32_16x16x32_bf16 v[66:69], v[122:125], v[230:233], v[66:69]
	v_mfma_f32_16x16x32_bf16 v[2:5], v[130:133], v[230:233], v[2:5]
	v_mfma_f32_16x16x32_bf16 v[90:93], v[126:129], v[186:189], v[90:93]
	v_mfma_f32_16x16x32_bf16 v[26:29], v[178:181], v[186:189], v[26:29]
	v_mfma_f32_16x16x32_bf16 v[82:85], v[126:129], v[218:221], v[82:85]
	v_mfma_f32_16x16x32_bf16 v[18:21], v[178:181], v[218:221], v[18:21]
	v_mfma_f32_16x16x32_bf16 v[74:77], v[126:129], v[226:229], v[74:77]
	v_mfma_f32_16x16x32_bf16 v[10:13], v[178:181], v[226:229], v[10:13]
	v_mfma_f32_16x16x32_bf16 v[66:69], v[126:129], v[234:237], v[66:69]
	v_mfma_f32_16x16x32_bf16 v[2:5], v[178:181], v[234:237], v[2:5]
	s_barrier
	s_add_i32 s72, 0, 0x18000
	s_add_i32 s73, 0, 0x1c000
	v_add_u32_e32 v118, s72, v214
	v_add_u32_e32 v178, s73, v214
	ds_read_b128 v[106:109], v118
	ds_read_b128 v[110:113], v118 offset:1024
	ds_read_b128 v[114:117], v118 offset:2048
	ds_read_b128 v[118:121], v118 offset:3072
	ds_read_b128 v[122:125], v178
	ds_read_b128 v[126:129], v178 offset:1024
	ds_read_b128 v[130:133], v178 offset:2048
	ds_read_b128 v[178:181], v178 offset:3072
	s_add_u32 s52, s52, 0x80000
	s_addc_u32 s53, s53, 0
	s_mov_b32 m0, s60
	v_lshl_add_u64 v[246:247], s[52:53], 0, v[172:173]
	ds_read_b128 v[182:185], v217 offset:32768
	ds_read_b128 v[186:189], v217 offset:33792
	ds_read_b128 v[190:193], v217 offset:34816
	ds_read_b128 v[218:221], v217 offset:35840
	ds_read_b128 v[222:225], v217 offset:36864
	ds_read_b128 v[226:229], v217 offset:37888
	ds_read_b128 v[230:233], v217 offset:38912
	ds_read_b128 v[234:237], v217 offset:39936
	global_load_lds_dwordx4 v[246:247], off
	v_lshl_add_u64 v[246:247], s[52:53], 0, v[170:171]
	s_mov_b32 m0, s61
	s_nop 0
	global_load_lds_dwordx4 v[246:247], off
	s_waitcnt vmcnt(8)
	s_waitcnt lgkmcnt(0)
	s_barrier
	s_waitcnt lgkmcnt(0)
	v_mfma_f32_16x16x32_bf16 v[154:157], v[106:109], v[182:185], v[154:157]
	v_mfma_f32_16x16x32_bf16 v[62:65], v[114:117], v[182:185], v[62:65]
	v_mfma_f32_16x16x32_bf16 v[150:153], v[106:109], v[190:193], v[150:153]
	v_mfma_f32_16x16x32_bf16 v[54:57], v[114:117], v[190:193], v[54:57]
	v_mfma_f32_16x16x32_bf16 v[142:145], v[106:109], v[222:225], v[142:145]
	v_mfma_f32_16x16x32_bf16 v[46:49], v[114:117], v[222:225], v[46:49]
	v_mfma_f32_16x16x32_bf16 v[102:105], v[106:109], v[230:233], v[102:105]
	v_mfma_f32_16x16x32_bf16 v[38:41], v[114:117], v[230:233], v[38:41]
	v_mfma_f32_16x16x32_bf16 v[154:157], v[110:113], v[186:189], v[154:157]
	v_mfma_f32_16x16x32_bf16 v[62:65], v[118:121], v[186:189], v[62:65]
	v_mfma_f32_16x16x32_bf16 v[150:153], v[110:113], v[218:221], v[150:153]
	v_mfma_f32_16x16x32_bf16 v[54:57], v[118:121], v[218:221], v[54:57]
	v_mfma_f32_16x16x32_bf16 v[142:145], v[110:113], v[226:229], v[142:145]
	v_mfma_f32_16x16x32_bf16 v[46:49], v[118:121], v[226:229], v[46:49]
	v_mfma_f32_16x16x32_bf16 v[102:105], v[110:113], v[234:237], v[102:105]
	v_mfma_f32_16x16x32_bf16 v[38:41], v[118:121], v[234:237], v[38:41]
	v_mfma_f32_16x16x32_bf16 v[134:137], v[122:125], v[182:185], v[134:137]
	v_mfma_f32_16x16x32_bf16 v[58:61], v[130:133], v[182:185], v[58:61]
	v_mfma_f32_16x16x32_bf16 v[146:149], v[122:125], v[190:193], v[146:149]
	v_mfma_f32_16x16x32_bf16 v[50:53], v[130:133], v[190:193], v[50:53]
	v_mfma_f32_16x16x32_bf16 v[138:141], v[122:125], v[222:225], v[138:141]
	v_mfma_f32_16x16x32_bf16 v[42:45], v[130:133], v[222:225], v[42:45]
	v_mfma_f32_16x16x32_bf16 v[98:101], v[122:125], v[230:233], v[98:101]
	v_mfma_f32_16x16x32_bf16 v[34:37], v[130:133], v[230:233], v[34:37]
	v_mfma_f32_16x16x32_bf16 v[134:137], v[126:129], v[186:189], v[134:137]
	v_mfma_f32_16x16x32_bf16 v[58:61], v[178:181], v[186:189], v[58:61]
	v_mfma_f32_16x16x32_bf16 v[146:149], v[126:129], v[218:221], v[146:149]
	v_mfma_f32_16x16x32_bf16 v[50:53], v[178:181], v[218:221], v[50:53]
	v_mfma_f32_16x16x32_bf16 v[138:141], v[126:129], v[226:229], v[138:141]
	v_mfma_f32_16x16x32_bf16 v[42:45], v[178:181], v[226:229], v[42:45]
	v_mfma_f32_16x16x32_bf16 v[98:101], v[126:129], v[234:237], v[98:101]
	v_mfma_f32_16x16x32_bf16 v[34:37], v[178:181], v[234:237], v[34:37]
	s_barrier
; #define PG8_STAGE(bufoff, gbase, voff) do { _Pragma("unroll") for (int _i = 0; _i < 2; ++_i) \
;         __builtin_amdgcn_global_load_lds((const unsigned*)((const char*)(gbase) + (voff)[_i]), (PG8_LAS unsigned*)(lds + (bufoff) + ldsw + _i * 8192), 16, 0, 0); } while (0)
; #define PG8_LDA(dst, b, h) do { _Pragma("unroll") for (int m = 0; m < 4; ++m) _Pragma("unroll") for (int k = 0; k < 2; ++k) dst[m][k] = *(const PG8_LAS bf16x8*)(lds + PG8_SA(b, h) + aoff + m * 2048 + k * 1024); } while (0)
; #define PG8_MMA(ai, bj, At, Bt) do { __builtin_amdgcn_s_setprio(1); _Pragma("unroll") for (int m = 0; m < 4; ++m) _Pragma("unroll") for (int n = 0; n < 2; ++n) _Pragma("unroll") for (int k = 0; k < 2; ++k) \
;         acc[ai][bj][m][n] = __builtin_amdgcn_mfma_f32_16x16x32_bf16(Bt[n][k], At[m][k], acc[ai][bj][m][n], 0, 0, 0); __builtin_amdgcn_s_setprio(0); } while (0)
; #define PG8_WAIT_V(n) asm volatile("s_waitcnt vmcnt(" #n ")" ::: "memory")
; #define PG8_WAIT_L(n) asm volatile("s_waitcnt lgkmcnt(" #n ")" ::: "memory")
; #define PG8_BAR __builtin_amdgcn_s_barrier()
; #define PG8_SCHED __builtin_amdgcn_sched_barrier(0)
;     __device__ __forceinline__ void operator()(const f32x4 (&acc)[2][2][4][2], const Unit& u, int wr, int wc, int fr, int fq) const {
;     ...
;                 for (int m = 0; m < 4; ++m) rs[ai][m] = rsqrtf(ss[row0 + ai * HALF + m * 16] * (1.f / 2048.f) + 1e-6f);
; template <class Epi, class Sched, bool ALIGN_EPI = false, bool SP2 = false>
; __device__ __forceinline__ void gemm_phase(PG8_LAS unsigned char* lds, const Gemm g, const Sched& S, const Epi& E, int wave_in) {
;     ...
;             PG8_LDA(At, 1, 1); PG8_STAGE(PG8_SB(1, 0), b3, voffB); PG8_STAGE(PG8_SB(1, 1), b3 + hstep, voffB); PG8_STAGE(PG8_SA(1, 0), a3, voffA);
;             PG8_WAIT_V(8); PG8_WAIT_L(0); PG8_BAR; PG8_MMA(1, 0, At, B0); PG8_MMA(1, 1, At, B1); PG8_BAR; PG8_SCHED;
	s_add_i32 s52, s72, s57
	v_lshl_add_u64 v[238:239], v[238:239], 0, s[84:85]
	s_mov_b32 m0, s52
	ds_read_b128 v[182:185], v217 offset:49152
	ds_read_b128 v[186:189], v217 offset:50176
	ds_read_b128 v[190:193], v217 offset:51200
	ds_read_b128 v[218:221], v217 offset:52224
	ds_read_b128 v[222:225], v217 offset:53248
	ds_read_b128 v[226:229], v217 offset:54272
	ds_read_b128 v[230:233], v217 offset:55296
	ds_read_b128 v[234:237], v217 offset:56320
	global_load_lds_dwordx4 v[238:239], off
	s_add_i32 m0, s52, 0x2000
	s_add_u32 s50, s50, 0x80080
	v_lshl_add_u64 v[238:239], v[240:241], 0, s[84:85]
	s_addc_u32 s51, s51, 0
	s_add_i32 s52, s73, s57
	global_load_lds_dwordx4 v[238:239], off
	v_lshl_add_u64 v[238:239], s[50:51], 0, v[0:1]
	s_mov_b32 m0, s52
	s_nop 0
	global_load_lds_dwordx4 v[238:239], off
	v_lshl_add_u64 v[238:239], s[50:51], 0, v[168:169]
	s_add_i32 m0, s52, 0x2000
	s_nop 0
	global_load_lds_dwordx4 v[238:239], off
	v_lshl_add_u64 v[238:239], v[242:243], 0, s[84:85]
	s_mov_b32 m0, s62
	s_nop 0
	global_load_lds_dwordx4 v[238:239], off
	v_lshl_add_u64 v[238:239], v[244:245], 0, s[84:85]
	s_mov_b32 m0, s63
	s_nop 0
	global_load_lds_dwordx4 v[238:239], off
	s_waitcnt vmcnt(8)
	s_waitcnt lgkmcnt(0)
	s_cmp_lg_u32 s71, 28
	s_cbranch_scc1 .Lup_nopf
	v_lshl_add_u32 v248, s66, 8, v213
	v_lshlrev_b32_e32 v248, 2, v248
	global_load_dword v206, v248, s[22:23]
	global_load_dword v207, v248, s[22:23] offset:64
	global_load_dword v208, v248, s[22:23] offset:128
	global_load_dword v209, v248, s[22:23] offset:192
	global_load_dword v210, v248, s[22:23] offset:512
	global_load_dword v211, v248, s[22:23] offset:576
	global_load_dword v250, v248, s[22:23] offset:640
	global_load_dword v251, v248, s[22:23] offset:704
.Lup_nopf:
	s_barrier
	s_waitcnt lgkmcnt(0)
	v_mfma_f32_16x16x32_bf16 v[94:97], v[106:109], v[182:185], v[94:97]
	v_mfma_f32_16x16x32_bf16 v[30:33], v[114:117], v[182:185], v[30:33]
	v_mfma_f32_16x16x32_bf16 v[86:89], v[106:109], v[190:193], v[86:89]
	v_mfma_f32_16x16x32_bf16 v[22:25], v[114:117], v[190:193], v[22:25]
	v_mfma_f32_16x16x32_bf16 v[78:81], v[106:109], v[222:225], v[78:81]
	v_mfma_f32_16x16x32_bf16 v[14:17], v[114:117], v[222:225], v[14:17]
	v_mfma_f32_16x16x32_bf16 v[70:73], v[106:109], v[230:233], v[70:73]
	v_mfma_f32_16x16x32_bf16 v[6:9], v[114:117], v[230:233], v[6:9]
	v_mfma_f32_16x16x32_bf16 v[94:97], v[110:113], v[186:189], v[94:97]
	v_mfma_f32_16x16x32_bf16 v[30:33], v[118:121], v[186:189], v[30:33]
	v_mfma_f32_16x16x32_bf16 v[86:89], v[110:113], v[218:221], v[86:89]
	v_mfma_f32_16x16x32_bf16 v[22:25], v[118:121], v[218:221], v[22:25]
	v_mfma_f32_16x16x32_bf16 v[78:81], v[110:113], v[226:229], v[78:81]
	v_mfma_f32_16x16x32_bf16 v[14:17], v[118:121], v[226:229], v[14:17]
	v_mfma_f32_16x16x32_bf16 v[70:73], v[110:113], v[234:237], v[70:73]
	v_mfma_f32_16x16x32_bf16 v[6:9], v[118:121], v[234:237], v[6:9]
	v_mfma_f32_16x16x32_bf16 v[90:93], v[122:125], v[182:185], v[90:93]
	v_mfma_f32_16x16x32_bf16 v[26:29], v[130:133], v[182:185], v[26:29]
	v_mfma_f32_16x16x32_bf16 v[82:85], v[122:125], v[190:193], v[82:85]
	v_mfma_f32_16x16x32_bf16 v[18:21], v[130:133], v[190:193], v[18:21]
	v_mfma_f32_16x16x32_bf16 v[74:77], v[122:125], v[222:225], v[74:77]
	v_mfma_f32_16x16x32_bf16 v[10:13], v[130:133], v[222:225], v[10:13]
	v_mfma_f32_16x16x32_bf16 v[66:69], v[122:125], v[230:233], v[66:69]
	v_mfma_f32_16x16x32_bf16 v[2:5], v[130:133], v[230:233], v[2:5]
	v_mfma_f32_16x16x32_bf16 v[90:93], v[126:129], v[186:189], v[90:93]
	v_mfma_f32_16x16x32_bf16 v[26:29], v[178:181], v[186:189], v[26:29]
	v_mfma_f32_16x16x32_bf16 v[82:85], v[126:129], v[218:221], v[82:85]
	v_mfma_f32_16x16x32_bf16 v[18:21], v[178:181], v[218:221], v[18:21]
	v_mfma_f32_16x16x32_bf16 v[74:77], v[126:129], v[226:229], v[74:77]
	v_mfma_f32_16x16x32_bf16 v[10:13], v[178:181], v[226:229], v[10:13]
	v_mfma_f32_16x16x32_bf16 v[66:69], v[126:129], v[234:237], v[66:69]
	v_mfma_f32_16x16x32_bf16 v[2:5], v[178:181], v[234:237], v[2:5]
	s_barrier
	s_add_i32 s71, s71, 2
	s_add_u32 s48, s48, 0x100
	s_addc_u32 s49, s49, 0
	s_add_u32 s69, s69, 0x100
	s_addc_u32 s70, s70, 0
	s_cmp_gt_u32 s71, 29
	s_cbranch_scc0 .LBB0_43
	s_and_b64 vcc, exec, s[24:25]
	s_cbranch_vccz .LBB0_46
	s_barrier
;     __device__ __forceinline__ void operator()(const f32x4 (&acc)[2][2][4][2], const Unit& u, int wr, int wc, int fr, int fq) const {
;     ...
;             float rs[2][4];
; #pragma unroll
;             for (int ai = 0; ai < 2; ++ai)
; #pragma unroll
;                 for (int m = 0; m < 4; ++m) rs[ai][m] = rsqrtf(ss[row0 + ai * HALF + m * 16] * (1.f / 2048.f) + 1e-6f);
; #pragma unroll
;             for (int ai = 0; ai < 2; ++ai) {
;                 const int slab = u.pm * 4 + ai * 2 + wr;
;                 if (fr < 2) {
; #pragma unroll
;                     for (int bj = 0; bj < 2; ++bj)
; #pragma unroll
;                         for (int n = 0; n < 2; ++n) *(f32x4*)(raw + (size_t)(slab * 4 + fr) * NUPc + tcol + bj * 128 + 4 * n) = acc[ai][bj][0][n] * rs[ai][0];
;                 }
;                 if (fr >= 14) {
; #pragma unroll
;                     for (int bj = 0; bj < 2; ++bj)
; #pragma unroll
;                         for (int n = 0; n < 2; ++n) *(f32x4*)(raw + (size_t)(slab * 4 + fr - 12) * NUPc + tcol + bj * 128 + 4 * n) = acc[ai][bj][3][n] * rs[ai][3];
;                 }
;             }
;     ...
;                 const f32x4 wg0 = *(const f32x4*)(bias + c), wg1 = *(const f32x4*)(bias + NUPc + c), wg2 = *(const f32x4*)(bias + 2 * NUPc + c), bg = *(const f32x4*)(xin + c);
;                 const f32x4 wv0 = *(const f32x4*)(bias + DFFc + c), wv1 = *(const f32x4*)(bias + NUPc + DFFc + c), wv2 = *(const f32x4*)(bias + 2 * NUPc + DFFc + c), bv = *(const f32x4*)(xin + DFFc + c);
.LBB0_46:
	v_lshl_or_b32 v201, s65, 7, v216
	v_lshlrev_b32_e32 v205, 2, v201
	global_load_dwordx4 v[218:221], v205, s[18:19]
	global_load_dwordx4 v[222:225], v205, s[20:21]
	global_load_dwordx4 v[226:229], v205, s[26:27]
	global_load_dwordx4 v[230:233], v205, s[28:29]
	global_load_dwordx4 v[234:237], v205, s[30:31]
	global_load_dwordx4 v[238:241], v205, s[38:39]
	global_load_dwordx4 v[242:245], v205, s[34:35]
	global_load_dwordx4 v[246:249], v205, s[36:37]
	v_lshl_add_u32 v186, s66, 8, v213
	v_ashrrev_i32_e32 v187, 31, v186
	v_lshl_add_u64 v[106:107], v[186:187], 2, s[22:23]
	s_waitcnt vmcnt(8)
	v_mov_b32_e32 v108, v206
	s_mov_b32 s67, 0x800000
	s_lshl_b32 s41, s66, 2
	s_add_i32 s41, s41, s56
	s_nop 0
	v_fmamk_f32 v108, v108, 0x3a000000, v197
	v_cmp_gt_f32_e32 vcc, s67, v108
	v_mul_f32_e32 v109, 0x4b800000, v108
	s_nop 0
	v_cndmask_b32_e32 v108, v108, v109, vcc
	v_rsq_f32_e32 v108, v108
	s_nop 0
	v_mul_f32_e32 v109, 0x45800000, v108
	v_cndmask_b32_e32 v188, v108, v109, vcc
	v_mov_b32_e32 v187, v207
	v_mov_b32_e32 v179, v208
	v_mov_b32_e32 v110, v209
	v_mov_b32_e32 v109, v210
	v_mov_b32_e32 v185, v211
	v_mov_b32_e32 v183, v250
	v_mov_b32_e32 v108, v251
	v_lshl_or_b32 v106, s65, 8, v216
	v_ashrrev_i32_e32 v107, 31, v106
	s_and_saveexec_b64 s[48:49], s[0:1]
	v_readlane_b32 s68, v254, 10
	v_readlane_b32 s69, v254, 11
	s_cbranch_execz .LBB0_48
	v_lshl_or_b32 v111, s41, 2, v212
	v_mov_b64_e32 v[116:117], s[16:17]
	s_mov_b32 s43, 0xb000
	v_mad_i64_i32 v[116:117], s[50:51], v111, s43, v[116:117]
	v_pk_mul_f32 v[114:115], v[156:157], v[188:189] op_sel_hi:[1,0]
	v_pk_mul_f32 v[112:113], v[154:155], v[188:189] op_sel_hi:[1,0]
	v_lshl_add_u64 v[116:117], v[106:107], 2, v[116:117]
	global_store_dwordx4 v[116:117], v[112:115], off
	s_nop 1
	v_pk_mul_f32 v[114:115], v[64:65], v[188:189] op_sel_hi:[1,0]
	v_pk_mul_f32 v[112:113], v[62:63], v[188:189] op_sel_hi:[1,0]
	global_store_dwordx4 v[116:117], v[112:115], off offset:16
	s_nop 1
	v_pk_mul_f32 v[114:115], v[136:137], v[188:189] op_sel_hi:[1,0]
	v_pk_mul_f32 v[112:113], v[134:135], v[188:189] op_sel_hi:[1,0]
	global_store_dwordx4 v[116:117], v[112:115], off offset:512
	s_nop 1
	v_pk_mul_f32 v[114:115], v[60:61], v[188:189] op_sel_hi:[1,0]
	v_pk_mul_f32 v[112:113], v[58:59], v[188:189] op_sel_hi:[1,0]
	global_store_dwordx4 v[116:117], v[112:115], off offset:528
.LBB0_48:
	s_or_b64 exec, exec, s[48:49]
	s_nop 0
	v_fmamk_f32 v110, v110, 0x3a000000, v197
	v_mul_f32_e32 v111, 0x4b800000, v110
	v_cmp_gt_f32_e32 vcc, s67, v110
	s_nop 1
	v_cndmask_b32_e32 v110, v110, v111, vcc
	v_rsq_f32_e32 v110, v110
	s_nop 0
	v_mul_f32_e32 v111, 0x45800000, v110
	v_cndmask_b32_e32 v184, v110, v111, vcc
	s_and_saveexec_b64 s[48:49], s[4:5]
	s_cbranch_execz .LBB0_50
	v_lshl_add_u32 v116, s41, 2, v215
	v_mov_b64_e32 v[114:115], s[16:17]
	s_mov_b32 s43, 0xb000
	v_mad_i64_i32 v[114:115], s[50:51], v116, s43, v[114:115]
	s_nop 0
	v_pk_mul_f32 v[112:113], v[104:105], v[184:185] op_sel_hi:[1,0]
	v_pk_mul_f32 v[110:111], v[102:103], v[184:185] op_sel_hi:[1,0]
	v_lshl_add_u64 v[114:115], v[106:107], 2, v[114:115]
	global_store_dwordx4 v[114:115], v[110:113], off
	s_nop 1
	v_pk_mul_f32 v[112:113], v[40:41], v[184:185] op_sel_hi:[1,0]
	v_pk_mul_f32 v[110:111], v[38:39], v[184:185] op_sel_hi:[1,0]
	global_store_dwordx4 v[114:115], v[110:113], off offset:16
	s_nop 1
	v_pk_mul_f32 v[112:113], v[100:101], v[184:185] op_sel_hi:[1,0]
	v_pk_mul_f32 v[110:111], v[98:99], v[184:185] op_sel_hi:[1,0]
	global_store_dwordx4 v[114:115], v[110:113], off offset:512
	s_nop 1
	v_pk_mul_f32 v[112:113], v[36:37], v[184:185] op_sel_hi:[1,0]
	v_pk_mul_f32 v[110:111], v[34:35], v[184:185] op_sel_hi:[1,0]
	global_store_dwordx4 v[114:115], v[110:113], off offset:528
.LBB0_50:
	s_or_b64 exec, exec, s[48:49]
	s_nop 0
	v_fmamk_f32 v109, v109, 0x3a000000, v197
	v_mul_f32_e32 v110, 0x4b800000, v109
	v_cmp_gt_f32_e32 vcc, s67, v109
	s_add_i32 s41, s41, 2
	s_nop 0
	v_cndmask_b32_e32 v109, v109, v110, vcc
	v_rsq_f32_e32 v109, v109
	s_nop 0
	v_mul_f32_e32 v110, 0x45800000, v109
	v_cndmask_b32_e32 v182, v109, v110, vcc
	s_and_saveexec_b64 s[48:49], s[0:1]
	s_cbranch_execz .LBB0_52
	v_lshl_or_b32 v109, s41, 2, v212
	v_mov_b64_e32 v[114:115], s[16:17]
	s_mov_b32 s43, 0xb000
	v_mad_i64_i32 v[114:115], s[50:51], v109, s43, v[114:115]
	s_nop 0
	v_pk_mul_f32 v[112:113], v[96:97], v[182:183] op_sel_hi:[1,0]
	v_pk_mul_f32 v[110:111], v[94:95], v[182:183] op_sel_hi:[1,0]
	v_lshl_add_u64 v[114:115], v[106:107], 2, v[114:115]
	global_store_dwordx4 v[114:115], v[110:113], off
	s_nop 1
	v_pk_mul_f32 v[112:113], v[32:33], v[182:183] op_sel_hi:[1,0]
	v_pk_mul_f32 v[110:111], v[30:31], v[182:183] op_sel_hi:[1,0]
	global_store_dwordx4 v[114:115], v[110:113], off offset:16
	s_nop 1
	v_pk_mul_f32 v[112:113], v[92:93], v[182:183] op_sel_hi:[1,0]
	v_pk_mul_f32 v[110:111], v[90:91], v[182:183] op_sel_hi:[1,0]
	global_store_dwordx4 v[114:115], v[110:113], off offset:512
	s_nop 1
	v_pk_mul_f32 v[112:113], v[28:29], v[182:183] op_sel_hi:[1,0]
	v_pk_mul_f32 v[110:111], v[26:27], v[182:183] op_sel_hi:[1,0]
	global_store_dwordx4 v[114:115], v[110:113], off offset:528

; template <class Epi, class Sched, bool ALIGN_EPI = false, bool SP2 = false>
; __device__ __forceinline__ void gemm_phase(PG8_LAS unsigned char* lds, const Gemm g, const Sched& S, const Epi& E, int wave_in) {
;     ...
;         const char* nA = has_next ? (const char*)g.A + (size_t)nxt.pm * tstepA : cA; const char* nB = has_next ? (const char*)g.Bt + (size_t)nxt.pn * tstep : cB;
;         for (int t = 0; t < nt; t += 2) {
;             const bool last = (t == nt - 2);
;             const char* a1 = cA + (size_t)(t + 1) * kstep;
;             const char* a2 = last ? nA : cA + (size_t)(t + 2) * kstep; const char* b2 = last ? nB : cB + (size_t)(t + 2) * kstep;
;             const char* a3 = a2 + kstep; const char* b3 = b2 + kstep;
;     ...
; #pragma unroll
;         for (int a = 0; a < 2; ++a)
; #pragma unroll
;             for (int b = 0; b < 2; ++b)
; #pragma unroll
;                 for (int m = 0; m < 4; ++m)
; #pragma unroll
;                     for (int n = 0; n < 2; ++n) acc[a][b][m][n] = (f32x4){0.f, 0.f, 0.f, 0.f};
;         cur = nxt; cA = nA; cB = nB; ++ui;
.LBB0_83:
	s_ashr_i32 s17, s16, 31
	s_lshl_b64 s[18:19], s[16:17], 20
	v_readlane_b32 s20, v253, 62
	v_readlane_b32 s21, v253, 63
	s_add_u32 s18, s20, s18
	s_addc_u32 s19, s21, s19
	s_and_b64 s[20:21], s[4:5], exec
	s_cselect_b32 s17, s19, s23
	s_cselect_b32 s42, s18, s22
	s_ashr_i32 s11, s10, 31
	s_lshl_b64 s[20:21], s[10:11], 19
	s_add_u32 s20, s28, s20
	s_addc_u32 s21, s29, s21
	s_and_b64 s[26:27], s[4:5], exec
	s_cselect_b32 s11, s21, s25
	s_cselect_b32 s43, s20, s24
	s_add_u32 s22, s22, 0x80080
	s_addc_u32 s23, s23, 0
	s_add_u32 s44, s24, 0x100
	v_mov_b32_e32 v2, 0
	s_addc_u32 s45, s25, 0
	s_mov_b32 s46, -2
	v_mov_b32_e32 v3, v2
	v_mov_b32_e32 v4, v2
	v_mov_b32_e32 v5, v2
	v_mov_b32_e32 v6, v2
	v_mov_b32_e32 v7, v2
	v_mov_b32_e32 v8, v2
	v_mov_b32_e32 v9, v2
	v_mov_b32_e32 v14, v2
	v_mov_b32_e32 v15, v2
	v_mov_b32_e32 v16, v2
	v_mov_b32_e32 v17, v2
	v_mov_b32_e32 v18, v2
	v_mov_b32_e32 v19, v2
	s_waitcnt vmcnt(0)
	v_mov_b32_e32 v20, v2
	v_mov_b32_e32 v21, v2
	v_mov_b32_e32 v30, v2
	v_mov_b32_e32 v31, v2
	v_mov_b32_e32 v32, v2
	v_mov_b32_e32 v33, v2
	v_mov_b32_e32 v34, v2
	v_mov_b32_e32 v35, v2
	v_mov_b32_e32 v36, v2
	v_mov_b32_e32 v37, v2
	v_mov_b32_e32 v46, v2
	v_mov_b32_e32 v47, v2
	v_mov_b32_e32 v48, v2
	v_mov_b32_e32 v49, v2
	v_mov_b32_e32 v50, v2
	v_mov_b32_e32 v51, v2
	v_mov_b32_e32 v52, v2
	v_mov_b32_e32 v53, v2
	v_mov_b32_e32 v10, v2
	v_mov_b32_e32 v11, v2
	v_mov_b32_e32 v12, v2
	v_mov_b32_e32 v13, v2
	v_mov_b32_e32 v22, v2
	v_mov_b32_e32 v23, v2
	v_mov_b32_e32 v24, v2
	v_mov_b32_e32 v25, v2
	v_mov_b32_e32 v26, v2
	v_mov_b32_e32 v27, v2
	v_mov_b32_e32 v28, v2
	v_mov_b32_e32 v29, v2
	v_mov_b32_e32 v38, v2
	v_mov_b32_e32 v39, v2
	v_mov_b32_e32 v40, v2
	v_mov_b32_e32 v41, v2
	v_mov_b32_e32 v42, v2
	v_mov_b32_e32 v43, v2
	v_mov_b32_e32 v44, v2
	v_mov_b32_e32 v45, v2
	v_mov_b32_e32 v54, v2
	v_mov_b32_e32 v55, v2
	v_mov_b32_e32 v56, v2
	v_mov_b32_e32 v57, v2
	v_mov_b32_e32 v58, v2
	v_mov_b32_e32 v59, v2
	v_mov_b32_e32 v60, v2
	v_mov_b32_e32 v61, v2
	v_mov_b32_e32 v62, v2
	v_mov_b32_e32 v63, v2
	v_mov_b32_e32 v64, v2
	v_mov_b32_e32 v65, v2
	v_mov_b32_e32 v66, v2
	v_mov_b32_e32 v67, v2
	v_mov_b32_e32 v68, v2
	v_mov_b32_e32 v69, v2
	v_mov_b32_e32 v70, v2
	v_mov_b32_e32 v71, v2
	v_mov_b32_e32 v72, v2
	v_mov_b32_e32 v73, v2
	v_mov_b32_e32 v78, v2
	v_mov_b32_e32 v79, v2
	v_mov_b32_e32 v80, v2
	v_mov_b32_e32 v81, v2
	v_mov_b32_e32 v82, v2
	v_mov_b32_e32 v83, v2
	v_mov_b32_e32 v84, v2
	v_mov_b32_e32 v85, v2
	v_mov_b32_e32 v94, v2
	v_mov_b32_e32 v95, v2
	v_mov_b32_e32 v96, v2
	v_mov_b32_e32 v97, v2
	v_mov_b32_e32 v98, v2
	v_mov_b32_e32 v99, v2
	v_mov_b32_e32 v100, v2
	v_mov_b32_e32 v101, v2
	v_mov_b32_e32 v110, v2
	v_mov_b32_e32 v111, v2
	v_mov_b32_e32 v112, v2
	v_mov_b32_e32 v113, v2
	v_mov_b32_e32 v114, v2
	v_mov_b32_e32 v115, v2
	v_mov_b32_e32 v116, v2
	v_mov_b32_e32 v117, v2
	v_mov_b32_e32 v74, v2
	v_mov_b32_e32 v75, v2
	v_mov_b32_e32 v76, v2
	v_mov_b32_e32 v77, v2
	v_mov_b32_e32 v86, v2
	v_mov_b32_e32 v87, v2
	v_mov_b32_e32 v88, v2
	v_mov_b32_e32 v89, v2
	v_mov_b32_e32 v90, v2
	v_mov_b32_e32 v91, v2
	v_mov_b32_e32 v92, v2
	v_mov_b32_e32 v93, v2
	v_mov_b32_e32 v102, v2
	v_mov_b32_e32 v103, v2
	v_mov_b32_e32 v104, v2
	v_mov_b32_e32 v105, v2
	v_mov_b32_e32 v106, v2
	v_mov_b32_e32 v107, v2
	v_mov_b32_e32 v108, v2
	v_mov_b32_e32 v109, v2
	v_mov_b32_e32 v118, v2
	v_mov_b32_e32 v119, v2
	v_mov_b32_e32 v120, v2
	v_mov_b32_e32 v121, v2
	v_mov_b32_e32 v122, v2
	v_mov_b32_e32 v123, v2
	v_mov_b32_e32 v124, v2
	v_mov_b32_e32 v125, v2
	v_mov_b32_e32 v126, v2
	v_mov_b32_e32 v127, v2
	v_mov_b32_e32 v128, v2
	v_mov_b32_e32 v129, v2
	s_nop 0
	s_nop 0
	s_nop 0
	s_nop 0
	s_nop 0
	s_nop 0
	s_nop 0
	s_nop 0
	s_nop 0
	s_nop 0
	s_nop 0
	s_nop 0
	s_nop 0
	s_nop 0
